# v38 + FOX tile loop: the 32 v_sub_f32 per tile that initialise the score accumulators (cum-forget bias minus running reference) issued as 16 v_pk_add_f32 with a negated broadcast operand
# speedup vs baseline: 1.0027x; 1.0027x over previous
.LBB0_489:
	s_add_i32 s31, s12, s30
	s_cmp_lt_i32 s30, s25
	s_cbranch_scc1 .LBB0_497
	ds_read_b128 v[68:71], v174 offset:128
	ds_read_b128 v[72:75], v174
	ds_read_b128 v[76:79], v174 offset:32
	ds_read_b128 v[198:201], v174 offset:160
	ds_read_b128 v[80:83], v174 offset:64
	ds_read_b128 v[202:205], v174 offset:192
	ds_read_b128 v[84:87], v174 offset:96
	ds_read_b128 v[206:209], v174 offset:224
	v_add_u32_e32 v164, v175, v176
	s_waitcnt lgkmcnt(5)
	v_pk_add_f32 v[90:91], v[78:79], v[194:195] op_sel_hi:[1,0] neg_lo:[0,1] neg_hi:[0,1]
	s_waitcnt lgkmcnt(1)
	v_pk_add_f32 v[98:99], v[86:87], v[194:195] op_sel_hi:[1,0] neg_lo:[0,1] neg_hi:[0,1]
	v_pk_add_f32 v[96:97], v[84:85], v[194:195] op_sel_hi:[1,0] neg_lo:[0,1] neg_hi:[0,1]
	v_pk_add_f32 v[88:89], v[76:77], v[194:195] op_sel_hi:[1,0] neg_lo:[0,1] neg_hi:[0,1]
	v_pk_add_f32 v[86:87], v[74:75], v[194:195] op_sel_hi:[1,0] neg_lo:[0,1] neg_hi:[0,1]
	v_pk_add_f32 v[84:85], v[72:73], v[194:195] op_sel_hi:[1,0] neg_lo:[0,1] neg_hi:[0,1]
	v_pk_add_f32 v[78:79], v[204:205], v[194:195] op_sel_hi:[1,0] neg_lo:[0,1] neg_hi:[0,1]
	v_pk_add_f32 v[76:77], v[202:203], v[194:195] op_sel_hi:[1,0] neg_lo:[0,1] neg_hi:[0,1]
	v_pk_add_f32 v[74:75], v[200:201], v[194:195] op_sel_hi:[1,0] neg_lo:[0,1] neg_hi:[0,1]
	v_pk_add_f32 v[72:73], v[198:199], v[194:195] op_sel_hi:[1,0] neg_lo:[0,1] neg_hi:[0,1]
	ds_read_b128 v[198:201], v164 offset:32768
	ds_read_b128 v[202:205], v164 offset:40960
	v_pk_add_f32 v[94:95], v[82:83], v[194:195] op_sel_hi:[1,0] neg_lo:[0,1] neg_hi:[0,1]
	v_pk_add_f32 v[92:93], v[80:81], v[194:195] op_sel_hi:[1,0] neg_lo:[0,1] neg_hi:[0,1]
	s_waitcnt lgkmcnt(2)
	v_pk_add_f32 v[82:83], v[208:209], v[194:195] op_sel_hi:[1,0] neg_lo:[0,1] neg_hi:[0,1]
	v_pk_add_f32 v[80:81], v[206:207], v[194:195] op_sel_hi:[1,0] neg_lo:[0,1] neg_hi:[0,1]
	v_pk_add_f32 v[70:71], v[70:71], v[194:195] op_sel_hi:[1,0] neg_lo:[0,1] neg_hi:[0,1]
	v_pk_add_f32 v[68:69], v[68:69], v[194:195] op_sel_hi:[1,0] neg_lo:[0,1] neg_hi:[0,1]
	s_waitcnt lgkmcnt(1)
	v_mfma_f32_32x32x16_bf16 v[84:99], v[198:201], v[100:103], v[84:99]
	v_add_u32_e32 v164, v175, v177
	s_cmp_le_i32 s13, s33
	s_waitcnt lgkmcnt(0)
	v_mfma_f32_32x32x16_bf16 v[68:83], v[202:205], v[100:103], v[68:83]
	ds_read_b128 v[198:201], v164 offset:32768
	ds_read_b128 v[202:205], v164 offset:40960
	v_add_u32_e32 v164, v175, v178
	s_waitcnt lgkmcnt(1)
	v_mfma_f32_32x32x16_bf16 v[84:99], v[198:201], v[104:107], v[84:99]
	s_waitcnt lgkmcnt(0)
	v_mfma_f32_32x32x16_bf16 v[68:83], v[202:205], v[104:107], v[68:83]
	ds_read_b128 v[198:201], v164 offset:32768
	ds_read_b128 v[202:205], v164 offset:40960
	v_add_u32_e32 v164, v175, v179
	s_waitcnt lgkmcnt(1)
	v_mfma_f32_32x32x16_bf16 v[84:99], v[198:201], v[108:111], v[84:99]
	s_waitcnt lgkmcnt(0)
	v_mfma_f32_32x32x16_bf16 v[68:83], v[202:205], v[108:111], v[68:83]
	ds_read_b128 v[198:201], v164 offset:32768
	ds_read_b128 v[202:205], v164 offset:40960
	v_add_u32_e32 v164, v175, v185
	s_waitcnt lgkmcnt(1)
	v_mfma_f32_32x32x16_bf16 v[84:99], v[198:201], v[112:115], v[84:99]
	s_waitcnt lgkmcnt(0)
	v_mfma_f32_32x32x16_bf16 v[68:83], v[202:205], v[112:115], v[68:83]
	ds_read_b128 v[198:201], v164 offset:32768
	ds_read_b128 v[202:205], v164 offset:40960
	v_add_u32_e32 v164, v175, v186
	s_waitcnt lgkmcnt(1)
	v_mfma_f32_32x32x16_bf16 v[84:99], v[198:201], v[116:119], v[84:99]
	s_waitcnt lgkmcnt(0)
	v_mfma_f32_32x32x16_bf16 v[68:83], v[202:205], v[116:119], v[68:83]
	ds_read_b128 v[198:201], v164 offset:32768
	ds_read_b128 v[202:205], v164 offset:40960
	v_add_u32_e32 v164, v175, v187
	s_waitcnt lgkmcnt(1)
	v_mfma_f32_32x32x16_bf16 v[84:99], v[198:201], v[120:123], v[84:99]
	s_waitcnt lgkmcnt(0)
	v_mfma_f32_32x32x16_bf16 v[68:83], v[202:205], v[120:123], v[68:83]
	ds_read_b128 v[198:201], v164 offset:32768
	ds_read_b128 v[202:205], v164 offset:40960
	v_add_u32_e32 v164, v175, v188
	s_waitcnt lgkmcnt(1)
	v_mfma_f32_32x32x16_bf16 v[84:99], v[198:201], v[124:127], v[84:99]
	s_waitcnt lgkmcnt(0)
	v_mfma_f32_32x32x16_bf16 v[68:83], v[202:205], v[124:127], v[68:83]
	ds_read_b128 v[198:201], v164 offset:32768
	ds_read_b128 v[202:205], v164 offset:40960
	s_waitcnt lgkmcnt(1)
	v_mfma_f32_32x32x16_bf16 v[84:99], v[198:201], v[128:131], v[84:99]
	s_waitcnt lgkmcnt(0)
	v_mfma_f32_32x32x16_bf16 v[68:83], v[202:205], v[128:131], v[68:83]
	s_cbranch_scc1 .LBB0_492
	v_cmp_gt_i32_e64 s[6:7], 26, v193
	v_cmp_gt_i32_e32 vcc, 27, v193
	v_cmp_gt_i32_e64 s[96:97], 25, v193
	v_cmp_gt_i32_e64 s[94:95], 24, v193
	s_nop 4
	v_cndmask_b32_e32 v99, v99, v222, vcc
	s_and_b64 vcc, vcc, s[6:7]
	v_cndmask_b32_e32 v98, v98, v222, vcc
	s_and_b64 vcc, vcc, s[96:97]
	s_mov_b32 s21, s93
	v_cmp_gt_i32_e64 s[92:93], 19, v193
	v_cndmask_b32_e32 v97, v97, v222, vcc
	s_and_b64 vcc, vcc, s[94:95]
	v_cmp_gt_i32_e64 s[90:91], 18, v193
	v_cndmask_b32_e32 v96, v96, v222, vcc
	s_and_b64 vcc, vcc, s[92:93]
	v_cmp_gt_i32_e64 s[88:89], 17, v193
	v_cndmask_b32_e32 v95, v95, v222, vcc
	s_and_b64 vcc, vcc, s[90:91]
	v_cmp_gt_i32_e64 s[86:87], 16, v193
	v_cndmask_b32_e32 v94, v94, v222, vcc
	s_and_b64 vcc, vcc, s[88:89]
	v_cmp_gt_i32_e64 s[84:85], 11, v193
	v_cndmask_b32_e32 v93, v93, v222, vcc
	s_and_b64 vcc, vcc, s[86:87]
	v_cmp_gt_i32_e64 s[82:83], 10, v193
	v_cndmask_b32_e32 v92, v92, v222, vcc
	s_and_b64 vcc, vcc, s[84:85]
	v_cmp_gt_i32_e64 s[80:81], 9, v193
	v_cndmask_b32_e32 v91, v91, v222, vcc
	s_and_b64 vcc, vcc, s[82:83]
	v_cmp_gt_i32_e64 s[78:79], 8, v193
	v_cndmask_b32_e32 v90, v90, v222, vcc
	s_and_b64 vcc, vcc, s[80:81]
	v_cmp_gt_i32_e64 s[76:77], 3, v193
	v_cndmask_b32_e32 v89, v89, v222, vcc
	s_and_b64 vcc, vcc, s[78:79]
	v_cmp_gt_i32_e64 s[74:75], 2, v193
	v_cndmask_b32_e32 v88, v88, v222, vcc
	s_and_b64 vcc, vcc, s[76:77]
	v_cmp_gt_i32_e64 s[72:73], 1, v193
	v_cndmask_b32_e32 v87, v87, v222, vcc
	s_and_b64 vcc, vcc, s[74:75]
	v_cmp_gt_i32_e64 s[70:71], 0, v193
	v_cndmask_b32_e32 v86, v86, v222, vcc
	s_and_b64 vcc, vcc, s[72:73]
	v_cndmask_b32_e32 v85, v85, v222, vcc
	s_and_b64 vcc, vcc, s[70:71]
	v_cmp_gt_i32_e64 s[68:69], 58, v193
	v_cndmask_b32_e32 v84, v84, v222, vcc
	v_cmp_gt_i32_e32 vcc, 59, v193
	v_cmp_gt_i32_e64 s[66:67], 57, v193
	v_cmp_gt_i32_e64 s[64:65], 56, v193
	v_cndmask_b32_e32 v83, v83, v222, vcc
	s_and_b64 vcc, vcc, s[68:69]
	v_cndmask_b32_e32 v82, v82, v222, vcc
	s_and_b64 vcc, vcc, s[66:67]
	v_cmp_gt_i32_e64 s[62:63], 51, v193
	v_cndmask_b32_e32 v81, v81, v222, vcc
	s_and_b64 vcc, vcc, s[64:65]
	v_cmp_gt_i32_e64 s[60:61], 50, v193
	v_cndmask_b32_e32 v80, v80, v222, vcc
	s_and_b64 vcc, vcc, s[62:63]
	v_cmp_gt_i32_e64 s[58:59], 49, v193
	v_cndmask_b32_e32 v79, v79, v222, vcc
	s_and_b64 vcc, vcc, s[60:61]
	v_cmp_gt_i32_e64 s[56:57], 48, v193
	v_cndmask_b32_e32 v78, v78, v222, vcc
	s_and_b64 vcc, vcc, s[58:59]
	v_cmp_gt_i32_e64 s[54:55], 43, v193
	v_cndmask_b32_e32 v77, v77, v222, vcc
	s_and_b64 vcc, vcc, s[56:57]
	v_cmp_gt_i32_e64 s[52:53], 42, v193
	v_cndmask_b32_e32 v76, v76, v222, vcc
	s_and_b64 vcc, vcc, s[54:55]
	v_cmp_gt_i32_e64 s[50:51], 41, v193
	v_cndmask_b32_e32 v75, v75, v222, vcc
	s_and_b64 vcc, vcc, s[52:53]
	v_cmp_gt_i32_e64 s[48:49], 40, v193
	v_cndmask_b32_e32 v74, v74, v222, vcc
	s_and_b64 vcc, vcc, s[50:51]
	v_cmp_gt_i32_e64 s[46:47], 35, v193
	v_cndmask_b32_e32 v73, v73, v222, vcc
	s_and_b64 vcc, vcc, s[48:49]
	v_cmp_gt_i32_e64 s[44:45], 34, v193
	v_cndmask_b32_e32 v72, v72, v222, vcc
	s_and_b64 vcc, vcc, s[46:47]
	v_cmp_gt_i32_e64 s[42:43], 33, v193
	v_cndmask_b32_e32 v71, v71, v222, vcc
	s_and_b64 vcc, vcc, s[44:45]
	v_cmp_gt_i32_e64 s[4:5], 32, v193
	v_cndmask_b32_e32 v70, v70, v222, vcc
	s_and_b64 vcc, vcc, s[42:43]
	s_mov_b32 s96, -2.0
	v_readlane_b32 s94, v255, 34
	v_cndmask_b32_e32 v69, v69, v222, vcc
	s_and_b64 vcc, vcc, s[4:5]
	s_mov_b32 s97, 0xc0400000
	v_readlane_b32 s95, v255, 35
	s_mov_b32 s93, s21
	v_readlane_b32 s86, v255, 46
	s_mov_b64 s[84:85], 0x6000
	s_movk_i32 s83, 0x6000
	v_cndmask_b32_e32 v68, v68, v222, vcc

.LBB0_505:
	ds_read_b128 v[68:71], v190 offset:128
	ds_read_b128 v[72:75], v190
	ds_read_b128 v[76:79], v190 offset:32
	ds_read_b128 v[198:201], v190 offset:160
	ds_read_b128 v[80:83], v190 offset:64
	ds_read_b128 v[202:205], v190 offset:192
	ds_read_b128 v[84:87], v190 offset:96
	ds_read_b128 v[206:209], v190 offset:224
	v_add_u32_e32 v164, v175, v176
	s_waitcnt lgkmcnt(5)
	v_pk_add_f32 v[90:91], v[78:79], v[194:195] op_sel_hi:[1,0] neg_lo:[0,1] neg_hi:[0,1]
	s_waitcnt lgkmcnt(1)
	v_pk_add_f32 v[98:99], v[86:87], v[194:195] op_sel_hi:[1,0] neg_lo:[0,1] neg_hi:[0,1]
	v_pk_add_f32 v[96:97], v[84:85], v[194:195] op_sel_hi:[1,0] neg_lo:[0,1] neg_hi:[0,1]
	v_pk_add_f32 v[88:89], v[76:77], v[194:195] op_sel_hi:[1,0] neg_lo:[0,1] neg_hi:[0,1]
	v_pk_add_f32 v[86:87], v[74:75], v[194:195] op_sel_hi:[1,0] neg_lo:[0,1] neg_hi:[0,1]
	v_pk_add_f32 v[84:85], v[72:73], v[194:195] op_sel_hi:[1,0] neg_lo:[0,1] neg_hi:[0,1]
	v_pk_add_f32 v[78:79], v[204:205], v[194:195] op_sel_hi:[1,0] neg_lo:[0,1] neg_hi:[0,1]
	v_pk_add_f32 v[76:77], v[202:203], v[194:195] op_sel_hi:[1,0] neg_lo:[0,1] neg_hi:[0,1]
	v_pk_add_f32 v[74:75], v[200:201], v[194:195] op_sel_hi:[1,0] neg_lo:[0,1] neg_hi:[0,1]
	v_pk_add_f32 v[72:73], v[198:199], v[194:195] op_sel_hi:[1,0] neg_lo:[0,1] neg_hi:[0,1]
	ds_read_b128 v[198:201], v164 offset:49152
	ds_read_b128 v[202:205], v164 offset:57344
	v_pk_add_f32 v[94:95], v[82:83], v[194:195] op_sel_hi:[1,0] neg_lo:[0,1] neg_hi:[0,1]
	v_pk_add_f32 v[92:93], v[80:81], v[194:195] op_sel_hi:[1,0] neg_lo:[0,1] neg_hi:[0,1]
	s_waitcnt lgkmcnt(2)
	v_pk_add_f32 v[82:83], v[208:209], v[194:195] op_sel_hi:[1,0] neg_lo:[0,1] neg_hi:[0,1]
	v_pk_add_f32 v[80:81], v[206:207], v[194:195] op_sel_hi:[1,0] neg_lo:[0,1] neg_hi:[0,1]
	v_pk_add_f32 v[70:71], v[70:71], v[194:195] op_sel_hi:[1,0] neg_lo:[0,1] neg_hi:[0,1]
	v_pk_add_f32 v[68:69], v[68:69], v[194:195] op_sel_hi:[1,0] neg_lo:[0,1] neg_hi:[0,1]
	s_waitcnt lgkmcnt(1)
	v_mfma_f32_32x32x16_bf16 v[84:99], v[198:201], v[100:103], v[84:99]
	v_add_u32_e32 v164, v175, v177
	s_sub_i32 s4, s13, 64
	s_cmp_le_i32 s4, s33
	s_waitcnt lgkmcnt(0)
	v_mfma_f32_32x32x16_bf16 v[68:83], v[202:205], v[100:103], v[68:83]
	ds_read_b128 v[198:201], v164 offset:49152
	ds_read_b128 v[202:205], v164 offset:57344
	v_add_u32_e32 v164, v175, v178
	s_waitcnt lgkmcnt(1)
	v_mfma_f32_32x32x16_bf16 v[84:99], v[198:201], v[104:107], v[84:99]
	s_waitcnt lgkmcnt(0)
	v_mfma_f32_32x32x16_bf16 v[68:83], v[202:205], v[104:107], v[68:83]
	ds_read_b128 v[198:201], v164 offset:49152
	ds_read_b128 v[202:205], v164 offset:57344
	v_add_u32_e32 v164, v175, v179
	s_waitcnt lgkmcnt(1)
	v_mfma_f32_32x32x16_bf16 v[84:99], v[198:201], v[108:111], v[84:99]
	s_waitcnt lgkmcnt(0)
	v_mfma_f32_32x32x16_bf16 v[68:83], v[202:205], v[108:111], v[68:83]
	ds_read_b128 v[198:201], v164 offset:49152
	ds_read_b128 v[202:205], v164 offset:57344
	v_add_u32_e32 v164, v175, v185
	s_waitcnt lgkmcnt(1)
	v_mfma_f32_32x32x16_bf16 v[84:99], v[198:201], v[112:115], v[84:99]
	s_waitcnt lgkmcnt(0)
	v_mfma_f32_32x32x16_bf16 v[68:83], v[202:205], v[112:115], v[68:83]
	ds_read_b128 v[198:201], v164 offset:49152
	ds_read_b128 v[202:205], v164 offset:57344
	v_add_u32_e32 v164, v175, v186
	s_waitcnt lgkmcnt(1)
	v_mfma_f32_32x32x16_bf16 v[84:99], v[198:201], v[116:119], v[84:99]
	s_waitcnt lgkmcnt(0)
	v_mfma_f32_32x32x16_bf16 v[68:83], v[202:205], v[116:119], v[68:83]
	ds_read_b128 v[198:201], v164 offset:49152
	ds_read_b128 v[202:205], v164 offset:57344
	v_add_u32_e32 v164, v175, v187
	s_waitcnt lgkmcnt(1)
	v_mfma_f32_32x32x16_bf16 v[84:99], v[198:201], v[120:123], v[84:99]
	s_waitcnt lgkmcnt(0)
	v_mfma_f32_32x32x16_bf16 v[68:83], v[202:205], v[120:123], v[68:83]
	ds_read_b128 v[198:201], v164 offset:49152
	ds_read_b128 v[202:205], v164 offset:57344
	v_add_u32_e32 v164, v175, v188
	s_waitcnt lgkmcnt(1)
	v_mfma_f32_32x32x16_bf16 v[84:99], v[198:201], v[124:127], v[84:99]
	s_waitcnt lgkmcnt(0)
	v_mfma_f32_32x32x16_bf16 v[68:83], v[202:205], v[124:127], v[68:83]
	ds_read_b128 v[198:201], v164 offset:49152
	ds_read_b128 v[202:205], v164 offset:57344
	s_waitcnt lgkmcnt(1)
	v_mfma_f32_32x32x16_bf16 v[84:99], v[198:201], v[128:131], v[84:99]
	s_waitcnt lgkmcnt(0)
	v_mfma_f32_32x32x16_bf16 v[68:83], v[202:205], v[128:131], v[68:83]
	s_cbranch_scc1 .LBB0_507
	v_add_u32_e32 v164, 64, v193
	v_cmp_gt_i32_e64 s[94:95], 26, v164
	v_cmp_gt_i32_e64 s[96:97], 27, v164
	s_mov_b32 s21, s93
	v_cmp_gt_i32_e64 s[92:93], 25, v164
	s_and_b64 s[94:95], s[96:97], s[94:95]
	v_cmp_gt_i32_e64 s[90:91], 24, v164
	s_and_b64 s[92:93], s[94:95], s[92:93]
	v_cmp_gt_i32_e64 s[88:89], 19, v164
	s_and_b64 s[90:91], s[92:93], s[90:91]
	v_cmp_gt_i32_e64 s[86:87], 18, v164
	s_and_b64 s[88:89], s[90:91], s[88:89]
	v_cmp_gt_i32_e64 s[84:85], 17, v164
	s_and_b64 s[86:87], s[88:89], s[86:87]
	v_cmp_gt_i32_e64 s[82:83], 16, v164
	s_and_b64 s[84:85], s[86:87], s[84:85]
	v_cmp_gt_i32_e64 s[80:81], 11, v164
	s_and_b64 s[82:83], s[84:85], s[82:83]
	v_cmp_gt_i32_e64 s[78:79], 10, v164
	s_and_b64 s[80:81], s[82:83], s[80:81]
	v_cmp_gt_i32_e64 s[76:77], 9, v164
	s_and_b64 s[78:79], s[80:81], s[78:79]
	v_cmp_gt_i32_e64 s[74:75], 8, v164
	s_and_b64 s[76:77], s[78:79], s[76:77]
	v_cmp_gt_i32_e64 s[72:73], 3, v164
	s_and_b64 s[74:75], s[76:77], s[74:75]
	v_cmp_gt_i32_e64 s[70:71], 2, v164
	s_and_b64 s[72:73], s[74:75], s[72:73]
	v_cmp_gt_i32_e64 s[6:7], 1, v164
	s_and_b64 s[70:71], s[72:73], s[70:71]
	v_cmp_gt_i32_e64 s[4:5], 0, v164
	s_and_b64 s[6:7], s[70:71], s[6:7]
	s_and_b64 s[4:5], s[6:7], s[4:5]
	v_cmp_gt_i32_e64 s[68:69], 58, v164
	v_cndmask_b32_e64 v84, v84, v222, s[4:5]
	v_cmp_gt_i32_e64 s[4:5], 59, v164
	v_cmp_gt_i32_e64 s[66:67], 57, v164
	v_cmp_gt_i32_e64 s[64:65], 56, v164
	v_cndmask_b32_e64 v83, v83, v222, s[4:5]
	s_and_b64 s[4:5], s[4:5], s[68:69]
	v_cndmask_b32_e64 v82, v82, v222, s[4:5]
	s_and_b64 s[4:5], s[4:5], s[66:67]
	v_cmp_gt_i32_e64 s[62:63], 51, v164
	v_cndmask_b32_e64 v81, v81, v222, s[4:5]
	s_and_b64 s[4:5], s[4:5], s[64:65]
	v_cmp_gt_i32_e64 s[60:61], 50, v164
	v_cndmask_b32_e64 v80, v80, v222, s[4:5]
	s_and_b64 s[4:5], s[4:5], s[62:63]
	v_cmp_gt_i32_e64 s[58:59], 49, v164
	v_cndmask_b32_e64 v79, v79, v222, s[4:5]
	s_and_b64 s[4:5], s[4:5], s[60:61]
	v_cmp_gt_i32_e64 s[56:57], 48, v164
	v_cndmask_b32_e64 v78, v78, v222, s[4:5]
	s_and_b64 s[4:5], s[4:5], s[58:59]
	v_cmp_gt_i32_e64 s[54:55], 43, v164
	v_cndmask_b32_e64 v77, v77, v222, s[4:5]
	s_and_b64 s[4:5], s[4:5], s[56:57]
	v_cmp_gt_i32_e64 s[52:53], 42, v164
	v_cndmask_b32_e64 v76, v76, v222, s[4:5]
	s_and_b64 s[4:5], s[4:5], s[54:55]
	v_cmp_gt_i32_e64 s[50:51], 41, v164
	v_cndmask_b32_e64 v75, v75, v222, s[4:5]
	s_and_b64 s[4:5], s[4:5], s[52:53]
	v_cmp_gt_i32_e64 s[48:49], 40, v164
	v_cndmask_b32_e64 v74, v74, v222, s[4:5]
	s_and_b64 s[4:5], s[4:5], s[50:51]
	v_cmp_gt_i32_e64 s[46:47], 35, v164
	v_cndmask_b32_e64 v73, v73, v222, s[4:5]
	s_and_b64 s[4:5], s[4:5], s[48:49]
	v_cmp_gt_i32_e64 s[44:45], 34, v164
	v_cndmask_b32_e64 v72, v72, v222, s[4:5]
	s_and_b64 s[4:5], s[4:5], s[46:47]
	v_cmp_gt_i32_e64 s[42:43], 33, v164
	v_cndmask_b32_e64 v71, v71, v222, s[4:5]
	s_and_b64 s[4:5], s[4:5], s[44:45]
	v_cmp_gt_i32_e32 vcc, 32, v164
	v_cndmask_b32_e64 v70, v70, v222, s[4:5]
	s_and_b64 s[4:5], s[4:5], s[42:43]
	v_cndmask_b32_e64 v99, v99, v222, s[96:97]
	s_mov_b32 s96, -2.0
	v_cndmask_b32_e64 v98, v98, v222, s[94:95]
	v_readlane_b32 s94, v255, 34
	s_and_b64 vcc, s[4:5], vcc
	s_mov_b32 s97, 0xc0400000
	v_readlane_b32 s95, v255, 35
	v_cndmask_b32_e64 v97, v97, v222, s[92:93]
	s_mov_b32 s93, s21
	v_cndmask_b32_e64 v96, v96, v222, s[90:91]
	v_cndmask_b32_e64 v95, v95, v222, s[88:89]
	v_cndmask_b32_e64 v94, v94, v222, s[86:87]
	v_readlane_b32 s86, v255, 46
	v_cndmask_b32_e64 v93, v93, v222, s[84:85]
	s_mov_b64 s[84:85], 0x6000
	v_cndmask_b32_e64 v92, v92, v222, s[82:83]
	s_movk_i32 s83, 0x6000
	v_cndmask_b32_e64 v91, v91, v222, s[80:81]
	v_cndmask_b32_e64 v90, v90, v222, s[78:79]
	v_cndmask_b32_e64 v89, v89, v222, s[76:77]
	v_cndmask_b32_e64 v88, v88, v222, s[74:75]
	v_cndmask_b32_e64 v87, v87, v222, s[72:73]
	v_cndmask_b32_e64 v86, v86, v222, s[70:71]
	v_cndmask_b32_e64 v85, v85, v222, s[6:7]
	v_cndmask_b32_e64 v69, v69, v222, s[4:5]
	v_cndmask_b32_e32 v68, v68, v222, vcc
